# attention loop: K/V LDS-DMA stage block moved from the loop head (right after the barrier) into the PV MFMA section
# speedup vs baseline: 1.0069x; 1.0069x over previous
.LBB0_1324:
	s_barrier
	s_add_i32 s73, s50, 3
.LBB0_1326:
	s_mul_hi_u32 s34, s77, 0xaaaaaaab
	s_lshr_b32 s34, s34, 1
	s_mul_i32 s34, s34, 0xc000
	v_subrev_u32_e32 v0, s34, v130
	s_add_i32 s34, s2, s36
	v_add_u32_e32 v0, s34, v0
	ds_read_b128 v[188:191], v0
	ds_read_b128 v[82:85], v0 offset:4096
	ds_read_b128 v[94:97], v0 offset:6144
	ds_read_b128 v[98:101], v0 offset:1024
	ds_read_b128 v[86:89], v0 offset:2048
	ds_read_b128 v[132:135], v0 offset:3072
	s_lshl_b32 s34, s49, 14
	v_add_u32_e32 v131, s34, v124
	s_waitcnt lgkmcnt(5)
	v_mfma_f32_16x16x32_bf16 v[188:191], v[188:191], v[10:13], v[150:153]
	ds_read_b128 v[78:81], v0 offset:5120
	s_waitcnt lgkmcnt(2)
	v_mfma_f32_16x16x32_bf16 v[136:139], v[86:89], v[10:13], v[150:153]
	ds_read_b128 v[86:89], v0 offset:7168
	v_mfma_f32_16x16x32_bf16 v[90:93], v[82:85], v[10:13], v[150:153]
	v_mfma_f32_16x16x32_bf16 v[94:97], v[94:97], v[10:13], v[150:153]
	ds_read_b128 v[82:85], v131 offset:49152
	ds_read_b128 v[102:105], v131 offset:51200
	v_mfma_f32_16x16x32_bf16 v[160:163], v[98:101], v[18:21], v[188:191]
	s_waitcnt lgkmcnt(4)
	v_mfma_f32_16x16x32_bf16 v[164:167], v[132:135], v[18:21], v[136:139]
	ds_read_b128 v[98:101], v131 offset:53248
	s_mov_b32 s34, 0x41000000
	v_cmp_lt_f32_e32 vcc, s34, v194
	s_cmp_lg_u64 vcc, 0
	s_cselect_b64 s[34:35], -1, 0
	s_cbranch_vccz .LBB0_1328
	v_cndmask_b32_e32 v132, 0, v194, vcc
	v_exp_f32_e64 v0, -v132
	v_sub_f32_e32 v74, v74, v132
	v_sub_f32_e32 v75, v75, v132
	v_sub_f32_e32 v76, v76, v132
	v_sub_f32_e32 v77, v77, v132
	v_sub_f32_e32 v70, v70, v132
	v_sub_f32_e32 v71, v71, v132
	v_sub_f32_e32 v72, v72, v132
	v_sub_f32_e32 v73, v73, v132
	v_sub_f32_e32 v22, v22, v132
	v_sub_f32_e32 v23, v23, v132
	v_sub_f32_e32 v24, v24, v132
	v_sub_f32_e32 v25, v25, v132
	v_sub_f32_e32 v26, v26, v132
	v_sub_f32_e32 v27, v27, v132
	v_sub_f32_e32 v28, v28, v132
	v_sub_f32_e32 v29, v29, v132
	v_add_f32_e32 v113, v113, v132
	v_xor_b32_e32 v150, 0x80000000, v113
	v_mov_b32_e32 v151, v150
	v_mov_b32_e32 v152, v150
	v_mov_b32_e32 v153, v150
	s_branch .LBB0_1329
.LBB0_1328:
.LBB0_1329:
	ds_read_b128 v[134:137], v131 offset:55296
	s_waitcnt lgkmcnt(5)
	v_mfma_f32_16x16x32_bf16 v[168:171], v[78:81], v[18:21], v[90:93]
	ds_read_b128 v[78:81], v131 offset:57344
	s_waitcnt lgkmcnt(5)
	v_mfma_f32_16x16x32_bf16 v[172:175], v[86:89], v[18:21], v[94:97]
	ds_read_b128 v[86:89], v131 offset:59392
	s_waitcnt lgkmcnt(5)
	v_mfma_f32_16x16x32_bf16 v[30:33], v[82:85], v[14:17], v[30:33]
	v_exp_f32_e32 v145, v74
	v_exp_f32_e32 v146, v75
	v_exp_f32_e32 v147, v76
	v_exp_f32_e32 v148, v77
	ds_read_b128 v[176:179], v131 offset:61440
	s_waitcnt lgkmcnt(5)
	v_mfma_f32_16x16x32_bf16 v[50:53], v[102:105], v[14:17], v[50:53]
	v_max3_f32 v195, v160, v161, v162
	v_max3_f32 v195, v195, v163, v164
	v_max3_f32 v195, v195, v165, v166
	v_max_f32_e32 v195, v195, v167
	ds_read_b128 v[82:85], v131 offset:63488
	s_waitcnt lgkmcnt(5)
	v_mfma_f32_16x16x32_bf16 v[42:45], v[98:101], v[14:17], v[42:45]
	s_cmp_ge_u32 s73, s71
	s_cbranch_scc1 .Latt_stgA_skip
	s_mul_hi_u32 s49, s50, 0xaaaaaaab
	s_lshr_b32 s49, s49, 1
	s_mul_i32 s49, s49, 0xc000
	s_sub_i32 s49, s31, s49
	s_add_i32 s49, s36, s49
	s_add_i32 s49, s2, s49
	s_lshl_b32 s51, s37, 14
	s_add_i32 s51, s76, s51
	s_mov_b32 m0, s49
	s_add_i32 s50, s51, 0xc000
	global_load_lds_dwordx4 v[114:115], off
	v_lshl_add_u64 v[192:193], v[114:115], 0, s[44:45]
	s_add_i32 m0, s49, 0x2000
	s_nop 0
	global_load_lds_dwordx4 v[192:193], off
	s_mov_b32 m0, s50
	s_nop 0
	global_load_lds_dwordx4 v[118:119], off
	s_add_i32 m0, s51, 0xe000
	s_nop 0
	global_load_lds_dwordx4 v[116:117], off
.Latt_stgA_skip:
	ds_read_b128 v[90:93], v131 offset:50176
	s_waitcnt lgkmcnt(5)
	v_mfma_f32_16x16x32_bf16 v[34:37], v[134:137], v[14:17], v[34:37]
	v_exp_f32_e32 v98, v70
	v_exp_f32_e32 v99, v71
	v_exp_f32_e32 v100, v72
	v_exp_f32_e32 v101, v73
	ds_read_b128 v[180:183], v131 offset:52224
	s_waitcnt lgkmcnt(5)
	v_mfma_f32_16x16x32_bf16 v[58:61], v[78:81], v[14:17], v[58:61]
	v_max3_f32 v194, v168, v169, v170
	v_max3_f32 v194, v194, v171, v172
	v_max3_f32 v194, v194, v173, v174
	v_max3_f32 v194, v194, v175, v195
	ds_read_b128 v[78:81], v131 offset:54272
	s_waitcnt lgkmcnt(5)
	v_mfma_f32_16x16x32_bf16 v[54:57], v[86:89], v[14:17], v[54:57]
	ds_read_b128 v[86:89], v131 offset:56320
	s_waitcnt lgkmcnt(5)
	v_mfma_f32_16x16x32_bf16 v[46:49], v[176:179], v[14:17], v[46:49]
	v_exp_f32_e32 v102, v22
	v_exp_f32_e32 v103, v23
	v_exp_f32_e32 v104, v24
	v_exp_f32_e32 v105, v25
	ds_read_b128 v[176:179], v131 offset:58368
	s_waitcnt lgkmcnt(5)
	v_mfma_f32_16x16x32_bf16 v[38:41], v[82:85], v[14:17], v[38:41]
	v_mfma_f32_16x16x32_bf16 v[2:5], v[154:157], v[14:17], v[2:5]
	v_mov_b32_e32 v158, v194
	s_nop 1
	v_permlane16_swap_b32_e32 v194, v158
	v_max_f32_e32 v194, v194, v158
	ds_read_b128 v[94:97], v131 offset:60416
	s_waitcnt lgkmcnt(5)
	v_mfma_f32_16x16x32_bf16 v[30:33], v[90:93], v[6:9], v[30:33]
	v_exp_f32_e32 v133, v26
	v_exp_f32_e32 v134, v27
	v_exp_f32_e32 v135, v28
	v_exp_f32_e32 v136, v29
	ds_read_b128 v[90:93], v131 offset:62464
	s_waitcnt lgkmcnt(5)
	v_mfma_f32_16x16x32_bf16 v[50:53], v[180:183], v[6:9], v[50:53]
	v_mov_b32_e32 v158, v194
	s_nop 1
	v_permlane32_swap_b32_e32 v194, v158
	v_max_f32_e32 v194, v194, v158
	ds_read_b128 v[180:183], v131 offset:64512
	s_waitcnt lgkmcnt(5)
	v_mfma_f32_16x16x32_bf16 v[42:45], v[78:81], v[6:9], v[42:45]
	s_waitcnt lgkmcnt(4)
	v_mfma_f32_16x16x32_bf16 v[34:37], v[86:89], v[6:9], v[34:37]
	v_cvt_pk_bf16_f32 v14, v145, v146
	v_cvt_pk_bf16_f32 v15, v147, v148
	v_cvt_pk_bf16_f32 v16, v98, v99
	v_cvt_pk_bf16_f32 v17, v100, v101
	v_cvt_pk_bf16_f32 v184, v102, v103
	v_cvt_pk_bf16_f32 v185, v104, v105
	v_cvt_pk_bf16_f32 v186, v133, v134
	v_cvt_pk_bf16_f32 v187, v135, v136
	s_waitcnt lgkmcnt(3)
	v_mfma_f32_16x16x32_bf16 v[58:61], v[176:179], v[6:9], v[58:61]
	s_waitcnt lgkmcnt(2)
	v_mfma_f32_16x16x32_bf16 v[54:57], v[94:97], v[6:9], v[54:57]
	s_waitcnt lgkmcnt(1)
	v_mfma_f32_16x16x32_bf16 v[46:49], v[90:93], v[6:9], v[46:49]
	s_waitcnt lgkmcnt(0)
	v_mfma_f32_16x16x32_bf16 v[38:41], v[180:183], v[6:9], v[38:41]
	v_mfma_f32_16x16x32_bf16 v[2:5], v[154:157], v[6:9], v[2:5]
	s_andn2_b64 vcc, exec, s[34:35]
	s_cbranch_vccnz .LBB0_1331
	v_sub_f32_e32 v160, v160, v132
	v_sub_f32_e32 v161, v161, v132
	v_sub_f32_e32 v162, v162, v132
	v_sub_f32_e32 v163, v163, v132
	v_sub_f32_e32 v164, v164, v132
	v_sub_f32_e32 v165, v165, v132
	v_sub_f32_e32 v166, v166, v132
	v_sub_f32_e32 v167, v167, v132
	v_sub_f32_e32 v168, v168, v132
	v_sub_f32_e32 v169, v169, v132
	v_sub_f32_e32 v170, v170, v132
	v_sub_f32_e32 v171, v171, v132
	v_sub_f32_e32 v172, v172, v132
	v_sub_f32_e32 v173, v173, v132
	v_sub_f32_e32 v174, v174, v132
	v_sub_f32_e32 v175, v175, v132
	v_sub_f32_e32 v194, v194, v132
	v_pk_mul_f32 v[40:41], v[0:1], v[40:41] op_sel_hi:[0,1]
	v_pk_mul_f32 v[48:49], v[0:1], v[48:49] op_sel_hi:[0,1]
	v_pk_mul_f32 v[56:57], v[0:1], v[56:57] op_sel_hi:[0,1]
	v_pk_mul_f32 v[60:61], v[0:1], v[60:61] op_sel_hi:[0,1]
	v_pk_mul_f32 v[36:37], v[0:1], v[36:37] op_sel_hi:[0,1]
	v_pk_mul_f32 v[44:45], v[0:1], v[44:45] op_sel_hi:[0,1]
	v_pk_mul_f32 v[52:53], v[0:1], v[52:53] op_sel_hi:[0,1]
	v_pk_mul_f32 v[32:33], v[0:1], v[32:33] op_sel_hi:[0,1]
	v_pk_mul_f32 v[38:39], v[0:1], v[38:39] op_sel_hi:[0,1]
	v_pk_mul_f32 v[46:47], v[0:1], v[46:47] op_sel_hi:[0,1]
	v_pk_mul_f32 v[54:55], v[0:1], v[54:55] op_sel_hi:[0,1]
	v_pk_mul_f32 v[58:59], v[0:1], v[58:59] op_sel_hi:[0,1]
	v_pk_mul_f32 v[34:35], v[0:1], v[34:35] op_sel_hi:[0,1]
	v_pk_mul_f32 v[42:43], v[0:1], v[42:43] op_sel_hi:[0,1]
	v_pk_mul_f32 v[50:51], v[0:1], v[50:51] op_sel_hi:[0,1]
	v_pk_mul_f32 v[30:31], v[0:1], v[30:31] op_sel_hi:[0,1]
	v_pk_mul_f32 v[4:5], v[0:1], v[4:5] op_sel_hi:[0,1]
	v_pk_mul_f32 v[2:3], v[0:1], v[2:3] op_sel_hi:[0,1]

.Latt_B_1324:
	s_barrier
	s_add_i32 s73, s50, 3
.Latt_B_1326:
	s_mul_hi_u32 s34, s77, 0xaaaaaaab
	s_lshr_b32 s34, s34, 1
	s_mul_i32 s34, s34, 0xc000
	v_subrev_u32_e32 v0, s34, v130
	s_add_i32 s34, s2, s36
	v_add_u32_e32 v0, s34, v0
	ds_read_b128 v[188:191], v0
	ds_read_b128 v[82:85], v0 offset:4096
	ds_read_b128 v[94:97], v0 offset:6144
	ds_read_b128 v[98:101], v0 offset:1024
	ds_read_b128 v[86:89], v0 offset:2048
	ds_read_b128 v[132:135], v0 offset:3072
	s_lshl_b32 s34, s49, 14
	v_add_u32_e32 v131, s34, v124
	s_waitcnt lgkmcnt(5)
	v_mfma_f32_16x16x32_bf16 v[188:191], v[188:191], v[10:13], v[150:153]
	ds_read_b128 v[78:81], v0 offset:5120
	s_waitcnt lgkmcnt(2)
	v_mfma_f32_16x16x32_bf16 v[136:139], v[86:89], v[10:13], v[150:153]
	ds_read_b128 v[86:89], v0 offset:7168
	v_mfma_f32_16x16x32_bf16 v[90:93], v[82:85], v[10:13], v[150:153]
	v_mfma_f32_16x16x32_bf16 v[94:97], v[94:97], v[10:13], v[150:153]
	ds_read_b128 v[82:85], v131 offset:49152
	ds_read_b128 v[102:105], v131 offset:51200
	v_mfma_f32_16x16x32_bf16 v[74:77], v[98:101], v[18:21], v[188:191]
	s_waitcnt lgkmcnt(4)
	v_mfma_f32_16x16x32_bf16 v[70:73], v[132:135], v[18:21], v[136:139]
	ds_read_b128 v[98:101], v131 offset:53248
	s_mov_b32 s34, 0x41000000
	v_cmp_lt_f32_e32 vcc, s34, v194
	s_cmp_lg_u64 vcc, 0
	s_cselect_b64 s[34:35], -1, 0
	s_cbranch_vccz .Latt_B_1328
	v_cndmask_b32_e32 v132, 0, v194, vcc
	v_exp_f32_e64 v0, -v132
	v_sub_f32_e32 v160, v160, v132
	v_sub_f32_e32 v161, v161, v132
	v_sub_f32_e32 v162, v162, v132
	v_sub_f32_e32 v163, v163, v132
	v_sub_f32_e32 v164, v164, v132
	v_sub_f32_e32 v165, v165, v132
	v_sub_f32_e32 v166, v166, v132
	v_sub_f32_e32 v167, v167, v132
	v_sub_f32_e32 v168, v168, v132
	v_sub_f32_e32 v169, v169, v132
	v_sub_f32_e32 v170, v170, v132
	v_sub_f32_e32 v171, v171, v132
	v_sub_f32_e32 v172, v172, v132
	v_sub_f32_e32 v173, v173, v132
	v_sub_f32_e32 v174, v174, v132
	v_sub_f32_e32 v175, v175, v132
	v_add_f32_e32 v113, v113, v132
	v_xor_b32_e32 v150, 0x80000000, v113
	v_mov_b32_e32 v151, v150
	v_mov_b32_e32 v152, v150
	v_mov_b32_e32 v153, v150
	s_branch .Latt_B_1329
.Latt_B_1328:
.Latt_B_1329:
	ds_read_b128 v[134:137], v131 offset:55296
	s_waitcnt lgkmcnt(5)
	v_mfma_f32_16x16x32_bf16 v[22:25], v[78:81], v[18:21], v[90:93]
	ds_read_b128 v[78:81], v131 offset:57344
	s_waitcnt lgkmcnt(5)
	v_mfma_f32_16x16x32_bf16 v[26:29], v[86:89], v[18:21], v[94:97]
	ds_read_b128 v[86:89], v131 offset:59392
	s_waitcnt lgkmcnt(5)
	v_mfma_f32_16x16x32_bf16 v[30:33], v[82:85], v[14:17], v[30:33]
	v_exp_f32_e32 v145, v160
	v_exp_f32_e32 v146, v161
	v_exp_f32_e32 v147, v162
	v_exp_f32_e32 v148, v163
	ds_read_b128 v[176:179], v131 offset:61440
	s_waitcnt lgkmcnt(5)
	v_mfma_f32_16x16x32_bf16 v[50:53], v[102:105], v[14:17], v[50:53]
	v_max3_f32 v195, v74, v75, v76
	v_max3_f32 v195, v195, v77, v70
	v_max3_f32 v195, v195, v71, v72
	v_max_f32_e32 v195, v195, v73
	ds_read_b128 v[82:85], v131 offset:63488
	s_waitcnt lgkmcnt(5)
	v_mfma_f32_16x16x32_bf16 v[42:45], v[98:101], v[14:17], v[42:45]
	s_cmp_ge_u32 s73, s71
	s_cbranch_scc1 .Latt_stgB_skip
	s_mul_hi_u32 s49, s50, 0xaaaaaaab
	s_lshr_b32 s49, s49, 1
	s_mul_i32 s49, s49, 0xc000
	s_sub_i32 s49, s31, s49
	s_add_i32 s49, s36, s49
	s_add_i32 s49, s2, s49
	s_lshl_b32 s51, s37, 14
	s_add_i32 s51, s76, s51
	s_mov_b32 m0, s49
	s_add_i32 s50, s51, 0xc000
	global_load_lds_dwordx4 v[114:115], off
	v_lshl_add_u64 v[192:193], v[114:115], 0, s[44:45]
	s_add_i32 m0, s49, 0x2000
	s_nop 0
	global_load_lds_dwordx4 v[192:193], off
	s_mov_b32 m0, s50
	s_nop 0
	global_load_lds_dwordx4 v[118:119], off
	s_add_i32 m0, s51, 0xe000
	s_nop 0
	global_load_lds_dwordx4 v[116:117], off
.Latt_stgB_skip:
	ds_read_b128 v[90:93], v131 offset:50176
	s_waitcnt lgkmcnt(5)
	v_mfma_f32_16x16x32_bf16 v[34:37], v[134:137], v[14:17], v[34:37]
	v_exp_f32_e32 v98, v164
	v_exp_f32_e32 v99, v165
	v_exp_f32_e32 v100, v166
	v_exp_f32_e32 v101, v167
	ds_read_b128 v[180:183], v131 offset:52224
	s_waitcnt lgkmcnt(5)
	v_mfma_f32_16x16x32_bf16 v[58:61], v[78:81], v[14:17], v[58:61]
	v_max3_f32 v194, v22, v23, v24
	v_max3_f32 v194, v194, v25, v26
	v_max3_f32 v194, v194, v27, v28
	v_max3_f32 v194, v194, v29, v195
	ds_read_b128 v[78:81], v131 offset:54272
	s_waitcnt lgkmcnt(5)
	v_mfma_f32_16x16x32_bf16 v[54:57], v[86:89], v[14:17], v[54:57]
	ds_read_b128 v[86:89], v131 offset:56320
	s_waitcnt lgkmcnt(5)
	v_mfma_f32_16x16x32_bf16 v[46:49], v[176:179], v[14:17], v[46:49]
	v_exp_f32_e32 v102, v168
	v_exp_f32_e32 v103, v169
	v_exp_f32_e32 v104, v170
	v_exp_f32_e32 v105, v171
	ds_read_b128 v[176:179], v131 offset:58368
	s_waitcnt lgkmcnt(5)
	v_mfma_f32_16x16x32_bf16 v[38:41], v[82:85], v[14:17], v[38:41]
	v_mfma_f32_16x16x32_bf16 v[2:5], v[154:157], v[14:17], v[2:5]
	v_mov_b32_e32 v158, v194
	s_nop 1
	v_permlane16_swap_b32_e32 v194, v158
	v_max_f32_e32 v194, v194, v158
	ds_read_b128 v[94:97], v131 offset:60416
	s_waitcnt lgkmcnt(5)
	v_mfma_f32_16x16x32_bf16 v[30:33], v[90:93], v[184:187], v[30:33]
	v_exp_f32_e32 v133, v172
	v_exp_f32_e32 v134, v173
	v_exp_f32_e32 v135, v174
	v_exp_f32_e32 v136, v175
	ds_read_b128 v[90:93], v131 offset:62464
	s_waitcnt lgkmcnt(5)
	v_mfma_f32_16x16x32_bf16 v[50:53], v[180:183], v[184:187], v[50:53]
	v_mov_b32_e32 v158, v194
	s_nop 1
	v_permlane32_swap_b32_e32 v194, v158
	v_max_f32_e32 v194, v194, v158
	ds_read_b128 v[180:183], v131 offset:64512
	s_waitcnt lgkmcnt(5)
	v_mfma_f32_16x16x32_bf16 v[42:45], v[78:81], v[184:187], v[42:45]
	s_waitcnt lgkmcnt(4)
	v_mfma_f32_16x16x32_bf16 v[34:37], v[86:89], v[184:187], v[34:37]
	v_cvt_pk_bf16_f32 v14, v145, v146
	v_cvt_pk_bf16_f32 v15, v147, v148
	v_cvt_pk_bf16_f32 v16, v98, v99
	v_cvt_pk_bf16_f32 v17, v100, v101
	v_cvt_pk_bf16_f32 v6, v102, v103
	v_cvt_pk_bf16_f32 v7, v104, v105
	v_cvt_pk_bf16_f32 v8, v133, v134
	v_cvt_pk_bf16_f32 v9, v135, v136
	s_waitcnt lgkmcnt(3)
	v_mfma_f32_16x16x32_bf16 v[58:61], v[176:179], v[184:187], v[58:61]
	s_waitcnt lgkmcnt(2)
	v_mfma_f32_16x16x32_bf16 v[54:57], v[94:97], v[184:187], v[54:57]
	s_waitcnt lgkmcnt(1)
	v_mfma_f32_16x16x32_bf16 v[46:49], v[90:93], v[184:187], v[46:49]
	s_waitcnt lgkmcnt(0)
	v_mfma_f32_16x16x32_bf16 v[38:41], v[180:183], v[184:187], v[38:41]
	v_mfma_f32_16x16x32_bf16 v[2:5], v[154:157], v[184:187], v[2:5]
	s_andn2_b64 vcc, exec, s[34:35]
	s_cbranch_vccnz .Latt_B_1331
	v_sub_f32_e32 v74, v74, v132
	v_sub_f32_e32 v75, v75, v132
	v_sub_f32_e32 v76, v76, v132
	v_sub_f32_e32 v77, v77, v132
	v_sub_f32_e32 v70, v70, v132
	v_sub_f32_e32 v71, v71, v132
	v_sub_f32_e32 v72, v72, v132
	v_sub_f32_e32 v73, v73, v132
	v_sub_f32_e32 v22, v22, v132
	v_sub_f32_e32 v23, v23, v132
	v_sub_f32_e32 v24, v24, v132
	v_sub_f32_e32 v25, v25, v132
	v_sub_f32_e32 v26, v26, v132
	v_sub_f32_e32 v27, v27, v132
	v_sub_f32_e32 v28, v28, v132
	v_sub_f32_e32 v29, v29, v132
	v_sub_f32_e32 v194, v194, v132
	v_pk_mul_f32 v[40:41], v[0:1], v[40:41] op_sel_hi:[0,1]
	v_pk_mul_f32 v[48:49], v[0:1], v[48:49] op_sel_hi:[0,1]
	v_pk_mul_f32 v[56:57], v[0:1], v[56:57] op_sel_hi:[0,1]
	v_pk_mul_f32 v[60:61], v[0:1], v[60:61] op_sel_hi:[0,1]
	v_pk_mul_f32 v[36:37], v[0:1], v[36:37] op_sel_hi:[0,1]
	v_pk_mul_f32 v[44:45], v[0:1], v[44:45] op_sel_hi:[0,1]
	v_pk_mul_f32 v[52:53], v[0:1], v[52:53] op_sel_hi:[0,1]
	v_pk_mul_f32 v[32:33], v[0:1], v[32:33] op_sel_hi:[0,1]
	v_pk_mul_f32 v[38:39], v[0:1], v[38:39] op_sel_hi:[0,1]
	v_pk_mul_f32 v[46:47], v[0:1], v[46:47] op_sel_hi:[0,1]
	v_pk_mul_f32 v[54:55], v[0:1], v[54:55] op_sel_hi:[0,1]
	v_pk_mul_f32 v[58:59], v[0:1], v[58:59] op_sel_hi:[0,1]
	v_pk_mul_f32 v[34:35], v[0:1], v[34:35] op_sel_hi:[0,1]
	v_pk_mul_f32 v[42:43], v[0:1], v[42:43] op_sel_hi:[0,1]
	v_pk_mul_f32 v[50:51], v[0:1], v[50:51] op_sel_hi:[0,1]
	v_pk_mul_f32 v[30:31], v[0:1], v[30:31] op_sel_hi:[0,1]
	v_pk_mul_f32 v[4:5], v[0:1], v[4:5] op_sel_hi:[0,1]
	v_pk_mul_f32 v[2:3], v[0:1], v[2:3] op_sel_hi:[0,1]
